# MLA attention epilogue stores written through (sc1) so the grid barrier's L2 write-back after P8 has nothing left to flush
# baseline (speedup 1.0000x reference)
.LBB0_1450:
	s_and_saveexec_b64 s[0:1], s[6:7]
	ds_write_b32 v191, v199
	s_or_b64 exec, exec, s[0:1]
	s_waitcnt lgkmcnt(0)
	ds_read_b32 v82, v188
	v_and_b32_e32 v84, 64, v184
	v_xor_b32_e32 v83, 1, v184
	v_add_u32_e32 v84, 64, v84
	s_lshl_b32 s0, s89, 11
	s_waitcnt lgkmcnt(0)
	v_rcp_f32_e32 v85, v82
	v_cmp_lt_i32_e32 vcc, v83, v84
	s_add_u32 s0, s26, s0
	s_addc_u32 s1, s4, 0
	v_cndmask_b32_e32 v82, v184, v83, vcc
	s_lshl_b32 s3, s97, 1
	v_lshlrev_b32_e32 v84, 2, v82
	v_mul_f32_e32 v18, v18, v85
	s_add_u32 s3, s0, s3
	ds_bpermute_b32 v83, v84, v18
	s_addc_u32 s5, s1, 0
	s_ashr_i32 s97, s96, 31
	s_lshl_b64 s[0:1], s[96:97], 11
	s_add_u32 s0, s3, s0
	v_and_b32_e32 v82, 1, v187
	s_addc_u32 s1, s5, s1
	v_cmp_eq_u32_e32 vcc, 0, v82
	v_lshlrev_b32_e32 v162, 11, v186
	v_lshlrev_b32_e32 v82, 1, v189
	s_and_saveexec_b64 s[6:7], vcc
	s_cbranch_execz .LBB0_1454
	s_waitcnt lgkmcnt(0)
	v_cvt_pk_bf16_f32 v18, v18, v83
	v_lshl_add_u64 v[86:87], s[0:1], 0, v[162:163]
	v_mov_b32_e32 v83, v163
	v_lshl_add_u64 v[86:87], v[86:87], 0, v[82:83]
	global_store_dword v[86:87], v18, off sc1
.LBB0_1454:
	s_or_b64 exec, exec, s[6:7]
	v_mul_f32_e32 v18, v34, v85
	ds_bpermute_b32 v34, v84, v18
	s_and_saveexec_b64 s[6:7], vcc
	s_cbranch_execz .LBB0_1456
	v_lshl_add_u64 v[86:87], s[0:1], 0, v[162:163]
	s_waitcnt lgkmcnt(1)
	v_mov_b32_e32 v83, v163
	v_lshl_add_u64 v[86:87], v[86:87], 0, v[82:83]
	s_waitcnt lgkmcnt(0)
	v_cvt_pk_bf16_f32 v18, v18, v34
	global_store_dword v[86:87], v18, off offset:64 sc1
.LBB0_1456:
	s_or_b64 exec, exec, s[6:7]
	v_mul_f32_e32 v18, v50, v85
	s_waitcnt lgkmcnt(0)
	ds_bpermute_b32 v34, v84, v18
	s_and_saveexec_b64 s[6:7], vcc
	s_cbranch_execz .LBB0_1458
	v_lshl_add_u64 v[86:87], s[0:1], 0, v[162:163]
	v_mov_b32_e32 v83, v163
	v_lshl_add_u64 v[86:87], v[86:87], 0, v[82:83]
	s_waitcnt lgkmcnt(0)
	v_cvt_pk_bf16_f32 v18, v18, v34
	global_store_dword v[86:87], v18, off offset:128 sc1
.LBB0_1458:
	s_or_b64 exec, exec, s[6:7]
	v_mul_f32_e32 v18, v66, v85
	s_waitcnt lgkmcnt(0)
	ds_bpermute_b32 v34, v84, v18
	s_and_saveexec_b64 s[6:7], vcc
	s_cbranch_execz .LBB0_1460
	v_lshl_add_u64 v[86:87], s[0:1], 0, v[162:163]
	v_mov_b32_e32 v83, v163
	v_lshl_add_u64 v[86:87], v[86:87], 0, v[82:83]
	s_waitcnt lgkmcnt(0)
	v_cvt_pk_bf16_f32 v18, v18, v34
	global_store_dword v[86:87], v18, off offset:192 sc1
.LBB0_1460:
	s_or_b64 exec, exec, s[6:7]
	ds_read_b32 v18, v188 offset:4
	v_or_b32_e32 v50, 1, v186
	v_lshlrev_b32_e32 v162, 11, v50
	s_waitcnt lgkmcnt(0)
	v_rcp_f32_e32 v18, v18
	s_nop 0
	v_mul_f32_e32 v19, v19, v18
	ds_bpermute_b32 v34, v84, v19
	s_and_saveexec_b64 s[6:7], vcc
	s_cbranch_execz .LBB0_1462
	v_lshl_add_u64 v[86:87], s[0:1], 0, v[162:163]
	v_mov_b32_e32 v83, v163
	v_lshl_add_u64 v[86:87], v[86:87], 0, v[82:83]
	s_waitcnt lgkmcnt(0)
	v_cvt_pk_bf16_f32 v19, v19, v34
	global_store_dword v[86:87], v19, off sc1
.LBB0_1462:
	s_or_b64 exec, exec, s[6:7]
	v_mul_f32_e32 v19, v35, v18
	s_waitcnt lgkmcnt(0)
	ds_bpermute_b32 v34, v84, v19
	s_and_saveexec_b64 s[6:7], vcc
	s_cbranch_execz .LBB0_1464
	s_waitcnt lgkmcnt(0)
	v_cvt_pk_bf16_f32 v19, v19, v34
	v_lshl_add_u64 v[34:35], s[0:1], 0, v[162:163]
	v_mov_b32_e32 v83, v163
	v_lshl_add_u64 v[34:35], v[34:35], 0, v[82:83]
	global_store_dword v[34:35], v19, off offset:64 sc1
.LBB0_1464:
	s_or_b64 exec, exec, s[6:7]
	v_mul_f32_e32 v19, v51, v18
	s_waitcnt lgkmcnt(0)
	ds_bpermute_b32 v34, v84, v19
	s_and_saveexec_b64 s[6:7], vcc
	s_cbranch_execz .LBB0_1466
	s_waitcnt lgkmcnt(0)
	v_cvt_pk_bf16_f32 v19, v19, v34
	v_lshl_add_u64 v[34:35], s[0:1], 0, v[162:163]
	v_mov_b32_e32 v83, v163
	v_lshl_add_u64 v[34:35], v[34:35], 0, v[82:83]
	global_store_dword v[34:35], v19, off offset:128 sc1
.LBB0_1466:
	s_or_b64 exec, exec, s[6:7]
	v_mul_f32_e32 v18, v67, v18
	ds_bpermute_b32 v19, v84, v18
	s_and_saveexec_b64 s[6:7], vcc
	s_cbranch_execz .LBB0_1468
	s_waitcnt lgkmcnt(0)
	v_cvt_pk_bf16_f32 v34, v18, v19
	v_lshl_add_u64 v[18:19], s[0:1], 0, v[162:163]
	v_mov_b32_e32 v83, v163
	v_lshl_add_u64 v[18:19], v[18:19], 0, v[82:83]
	global_store_dword v[18:19], v34, off offset:192 sc1
.LBB0_1468:
	s_or_b64 exec, exec, s[6:7]
	ds_read_b32 v18, v188 offset:8
	s_waitcnt lgkmcnt(2)
	v_or_b32_e32 v34, 2, v186
	v_lshlrev_b32_e32 v162, 11, v34
	s_waitcnt lgkmcnt(0)
	v_rcp_f32_e32 v18, v18
	s_nop 0
	v_mul_f32_e32 v19, v20, v18
	ds_bpermute_b32 v20, v84, v19
	s_and_saveexec_b64 s[6:7], vcc
	s_cbranch_execz .LBB0_1470
	v_lshl_add_u64 v[34:35], s[0:1], 0, v[162:163]
	v_mov_b32_e32 v83, v163
	v_lshl_add_u64 v[34:35], v[34:35], 0, v[82:83]
	s_waitcnt lgkmcnt(0)
	v_cvt_pk_bf16_f32 v19, v19, v20
	global_store_dword v[34:35], v19, off sc1
.LBB0_1470:
	s_or_b64 exec, exec, s[6:7]
	v_mul_f32_e32 v19, v36, v18
	s_waitcnt lgkmcnt(0)
	ds_bpermute_b32 v20, v84, v19
	s_and_saveexec_b64 s[6:7], vcc
	s_cbranch_execz .LBB0_1472
	v_lshl_add_u64 v[34:35], s[0:1], 0, v[162:163]
	v_mov_b32_e32 v83, v163
	v_lshl_add_u64 v[34:35], v[34:35], 0, v[82:83]
	s_waitcnt lgkmcnt(0)
	v_cvt_pk_bf16_f32 v19, v19, v20
	global_store_dword v[34:35], v19, off offset:64 sc1
.LBB0_1472:
	s_or_b64 exec, exec, s[6:7]
	v_mul_f32_e32 v19, v52, v18
	s_waitcnt lgkmcnt(0)
	ds_bpermute_b32 v20, v84, v19
	s_and_saveexec_b64 s[6:7], vcc
	s_cbranch_execz .LBB0_1474
	v_lshl_add_u64 v[34:35], s[0:1], 0, v[162:163]
	v_mov_b32_e32 v83, v163
	v_lshl_add_u64 v[34:35], v[34:35], 0, v[82:83]
	s_waitcnt lgkmcnt(0)
	v_cvt_pk_bf16_f32 v19, v19, v20
	global_store_dword v[34:35], v19, off offset:128 sc1
.LBB0_1474:
	s_or_b64 exec, exec, s[6:7]
	v_mul_f32_e32 v18, v68, v18
	ds_bpermute_b32 v19, v84, v18
	s_and_saveexec_b64 s[6:7], vcc
	s_cbranch_execz .LBB0_1476
	s_waitcnt lgkmcnt(0)
	v_cvt_pk_bf16_f32 v20, v18, v19
	v_lshl_add_u64 v[18:19], s[0:1], 0, v[162:163]
	v_mov_b32_e32 v83, v163
	v_lshl_add_u64 v[18:19], v[18:19], 0, v[82:83]
	global_store_dword v[18:19], v20, off offset:192 sc1
.LBB0_1476:
	s_or_b64 exec, exec, s[6:7]
	ds_read_b32 v18, v188 offset:12
	s_waitcnt lgkmcnt(0)
	v_rcp_f32_e32 v18, v18
	s_nop 0
	v_mul_f32_e32 v19, v21, v18
	ds_bpermute_b32 v20, v84, v19
	v_or_b32_e32 v21, 3, v186
	v_lshlrev_b32_e32 v162, 11, v21
	s_and_saveexec_b64 s[6:7], vcc
	s_cbranch_execz .LBB0_1478
	s_waitcnt lgkmcnt(0)
	v_cvt_pk_bf16_f32 v19, v19, v20
	v_lshl_add_u64 v[20:21], s[0:1], 0, v[162:163]
	v_mov_b32_e32 v83, v163
	v_lshl_add_u64 v[20:21], v[20:21], 0, v[82:83]
	global_store_dword v[20:21], v19, off sc1
.LBB0_1478:
	s_or_b64 exec, exec, s[6:7]
	v_mul_f32_e32 v19, v37, v18
	s_waitcnt lgkmcnt(0)
	ds_bpermute_b32 v20, v84, v19
	s_and_saveexec_b64 s[6:7], vcc
	s_cbranch_execz .LBB0_1480
	s_waitcnt lgkmcnt(0)
	v_cvt_pk_bf16_f32 v19, v19, v20
	v_lshl_add_u64 v[20:21], s[0:1], 0, v[162:163]
	v_mov_b32_e32 v83, v163
	v_lshl_add_u64 v[20:21], v[20:21], 0, v[82:83]
	global_store_dword v[20:21], v19, off offset:64 sc1
.LBB0_1480:
	s_or_b64 exec, exec, s[6:7]
	v_mul_f32_e32 v19, v53, v18
	s_waitcnt lgkmcnt(0)
	ds_bpermute_b32 v20, v84, v19
	s_and_saveexec_b64 s[6:7], vcc
	s_cbranch_execz .LBB0_1482
	s_waitcnt lgkmcnt(0)
	v_cvt_pk_bf16_f32 v19, v19, v20
	v_lshl_add_u64 v[20:21], s[0:1], 0, v[162:163]
	v_mov_b32_e32 v83, v163
	v_lshl_add_u64 v[20:21], v[20:21], 0, v[82:83]
	global_store_dword v[20:21], v19, off offset:128 sc1
.LBB0_1482:
	s_or_b64 exec, exec, s[6:7]
	v_mul_f32_e32 v18, v69, v18
	ds_bpermute_b32 v19, v84, v18
	s_and_saveexec_b64 s[6:7], vcc
	s_cbranch_execz .LBB0_1484
	s_waitcnt lgkmcnt(0)
	v_cvt_pk_bf16_f32 v20, v18, v19
	v_lshl_add_u64 v[18:19], s[0:1], 0, v[162:163]
	v_mov_b32_e32 v83, v163
	v_lshl_add_u64 v[18:19], v[18:19], 0, v[82:83]
	global_store_dword v[18:19], v20, off offset:192 sc1
.LBB0_1484:
	s_or_b64 exec, exec, s[6:7]
	ds_read_b32 v18, v188 offset:32
	v_or_b32_e32 v21, 8, v186
	v_lshlrev_b32_e32 v162, 11, v21
	s_waitcnt lgkmcnt(0)
	v_rcp_f32_e32 v18, v18
	s_nop 0
	v_mul_f32_e32 v19, v22, v18
	ds_bpermute_b32 v20, v84, v19
	s_and_saveexec_b64 s[6:7], vcc
	s_cbranch_execz .LBB0_1486
	s_waitcnt lgkmcnt(0)
	v_cvt_pk_bf16_f32 v19, v19, v20
	v_lshl_add_u64 v[20:21], s[0:1], 0, v[162:163]
	v_mov_b32_e32 v83, v163
	v_lshl_add_u64 v[20:21], v[20:21], 0, v[82:83]
	global_store_dword v[20:21], v19, off sc1
.LBB0_1486:
	s_or_b64 exec, exec, s[6:7]
	v_mul_f32_e32 v19, v38, v18
	s_waitcnt lgkmcnt(0)
	ds_bpermute_b32 v20, v84, v19
	s_and_saveexec_b64 s[6:7], vcc
	s_cbranch_execz .LBB0_1488
	s_waitcnt lgkmcnt(0)
	v_cvt_pk_bf16_f32 v19, v19, v20
	v_lshl_add_u64 v[20:21], s[0:1], 0, v[162:163]
	v_mov_b32_e32 v83, v163
	v_lshl_add_u64 v[20:21], v[20:21], 0, v[82:83]
	global_store_dword v[20:21], v19, off offset:64 sc1
.LBB0_1488:
	s_or_b64 exec, exec, s[6:7]
	v_mul_f32_e32 v19, v54, v18
	s_waitcnt lgkmcnt(0)
	ds_bpermute_b32 v20, v84, v19
	s_and_saveexec_b64 s[6:7], vcc
	s_cbranch_execz .LBB0_1490
	s_waitcnt lgkmcnt(0)
	v_cvt_pk_bf16_f32 v19, v19, v20
	v_lshl_add_u64 v[20:21], s[0:1], 0, v[162:163]
	v_mov_b32_e32 v83, v163
	v_lshl_add_u64 v[20:21], v[20:21], 0, v[82:83]
	global_store_dword v[20:21], v19, off offset:128 sc1
.LBB0_1490:
	s_or_b64 exec, exec, s[6:7]
	v_mul_f32_e32 v18, v70, v18
	ds_bpermute_b32 v19, v84, v18
	s_and_saveexec_b64 s[6:7], vcc
	s_cbranch_execz .LBB0_1492
	s_waitcnt lgkmcnt(0)
	v_cvt_pk_bf16_f32 v20, v18, v19
	v_lshl_add_u64 v[18:19], s[0:1], 0, v[162:163]
	v_mov_b32_e32 v83, v163
	v_lshl_add_u64 v[18:19], v[18:19], 0, v[82:83]
	global_store_dword v[18:19], v20, off offset:192 sc1
.LBB0_1492:
	s_or_b64 exec, exec, s[6:7]
	ds_read_b32 v18, v188 offset:36
	v_or_b32_e32 v21, 9, v186
	v_lshlrev_b32_e32 v162, 11, v21
	s_waitcnt lgkmcnt(0)
	v_rcp_f32_e32 v18, v18
	s_nop 0
	v_mul_f32_e32 v19, v23, v18
	ds_bpermute_b32 v20, v84, v19
	s_and_saveexec_b64 s[6:7], vcc
	s_cbranch_execz .LBB0_1494
	s_waitcnt lgkmcnt(0)
	v_cvt_pk_bf16_f32 v19, v19, v20
	v_lshl_add_u64 v[20:21], s[0:1], 0, v[162:163]
	v_mov_b32_e32 v83, v163
	v_lshl_add_u64 v[20:21], v[20:21], 0, v[82:83]
	global_store_dword v[20:21], v19, off sc1
.LBB0_1494:
	s_or_b64 exec, exec, s[6:7]
	v_mul_f32_e32 v19, v39, v18
	s_waitcnt lgkmcnt(0)
	ds_bpermute_b32 v20, v84, v19
	s_and_saveexec_b64 s[6:7], vcc
	s_cbranch_execz .LBB0_1496
	s_waitcnt lgkmcnt(0)
	v_cvt_pk_bf16_f32 v19, v19, v20
	v_lshl_add_u64 v[20:21], s[0:1], 0, v[162:163]
	v_mov_b32_e32 v83, v163
	v_lshl_add_u64 v[20:21], v[20:21], 0, v[82:83]
	global_store_dword v[20:21], v19, off offset:64 sc1
.LBB0_1496:
	s_or_b64 exec, exec, s[6:7]
	v_mul_f32_e32 v19, v55, v18
	s_waitcnt lgkmcnt(0)
	ds_bpermute_b32 v20, v84, v19
	s_and_saveexec_b64 s[6:7], vcc
	s_cbranch_execz .LBB0_1498
	s_waitcnt lgkmcnt(0)
	v_cvt_pk_bf16_f32 v19, v19, v20
	v_lshl_add_u64 v[20:21], s[0:1], 0, v[162:163]
	v_mov_b32_e32 v83, v163
	v_lshl_add_u64 v[20:21], v[20:21], 0, v[82:83]
	global_store_dword v[20:21], v19, off offset:128 sc1
.LBB0_1498:
	s_or_b64 exec, exec, s[6:7]
	v_mul_f32_e32 v18, v71, v18
	ds_bpermute_b32 v19, v84, v18
	s_and_saveexec_b64 s[6:7], vcc
	s_cbranch_execz .LBB0_1500
	s_waitcnt lgkmcnt(0)
	v_cvt_pk_bf16_f32 v20, v18, v19
	v_lshl_add_u64 v[18:19], s[0:1], 0, v[162:163]
	v_mov_b32_e32 v83, v163
	v_lshl_add_u64 v[18:19], v[18:19], 0, v[82:83]
	global_store_dword v[18:19], v20, off offset:192 sc1
.LBB0_1500:
	s_or_b64 exec, exec, s[6:7]
	ds_read_b32 v18, v188 offset:40
	v_or_b32_e32 v21, 10, v186
	v_lshlrev_b32_e32 v162, 11, v21
	s_waitcnt lgkmcnt(0)
	v_rcp_f32_e32 v18, v18
	s_nop 0
	v_mul_f32_e32 v19, v24, v18
	ds_bpermute_b32 v20, v84, v19
	s_and_saveexec_b64 s[6:7], vcc
	s_cbranch_execz .LBB0_1502
	s_waitcnt lgkmcnt(0)
	v_cvt_pk_bf16_f32 v19, v19, v20
	v_lshl_add_u64 v[20:21], s[0:1], 0, v[162:163]
	v_mov_b32_e32 v83, v163
	v_lshl_add_u64 v[20:21], v[20:21], 0, v[82:83]
	global_store_dword v[20:21], v19, off sc1
.LBB0_1502:
	s_or_b64 exec, exec, s[6:7]
	v_mul_f32_e32 v19, v40, v18
	s_waitcnt lgkmcnt(0)
	ds_bpermute_b32 v20, v84, v19
	s_and_saveexec_b64 s[6:7], vcc
	s_cbranch_execz .LBB0_1504
	s_waitcnt lgkmcnt(0)
	v_cvt_pk_bf16_f32 v19, v19, v20
	v_lshl_add_u64 v[20:21], s[0:1], 0, v[162:163]
	v_mov_b32_e32 v83, v163
	v_lshl_add_u64 v[20:21], v[20:21], 0, v[82:83]
	global_store_dword v[20:21], v19, off offset:64 sc1
.LBB0_1504:
	s_or_b64 exec, exec, s[6:7]
	v_mul_f32_e32 v19, v56, v18
	s_waitcnt lgkmcnt(0)
	ds_bpermute_b32 v20, v84, v19
	s_and_saveexec_b64 s[6:7], vcc
	s_cbranch_execz .LBB0_1506
	s_waitcnt lgkmcnt(0)
	v_cvt_pk_bf16_f32 v19, v19, v20
	v_lshl_add_u64 v[20:21], s[0:1], 0, v[162:163]
	v_mov_b32_e32 v83, v163
	v_lshl_add_u64 v[20:21], v[20:21], 0, v[82:83]
	global_store_dword v[20:21], v19, off offset:128 sc1
.LBB0_1506:
	s_or_b64 exec, exec, s[6:7]
	v_mul_f32_e32 v18, v72, v18
	ds_bpermute_b32 v19, v84, v18
	s_and_saveexec_b64 s[6:7], vcc
	s_cbranch_execz .LBB0_1508
	s_waitcnt lgkmcnt(0)
	v_cvt_pk_bf16_f32 v20, v18, v19
	v_lshl_add_u64 v[18:19], s[0:1], 0, v[162:163]
	v_mov_b32_e32 v83, v163
	v_lshl_add_u64 v[18:19], v[18:19], 0, v[82:83]
	global_store_dword v[18:19], v20, off offset:192 sc1
.LBB0_1508:
	s_or_b64 exec, exec, s[6:7]
	ds_read_b32 v18, v188 offset:44
	v_or_b32_e32 v21, 11, v186
	v_lshlrev_b32_e32 v162, 11, v21
	s_waitcnt lgkmcnt(0)
	v_rcp_f32_e32 v18, v18
	s_nop 0
	v_mul_f32_e32 v19, v25, v18
	ds_bpermute_b32 v20, v84, v19
	s_and_saveexec_b64 s[6:7], vcc
	s_cbranch_execz .LBB0_1510
	s_waitcnt lgkmcnt(0)
	v_cvt_pk_bf16_f32 v19, v19, v20
	v_lshl_add_u64 v[20:21], s[0:1], 0, v[162:163]
	v_mov_b32_e32 v83, v163
	v_lshl_add_u64 v[20:21], v[20:21], 0, v[82:83]
	global_store_dword v[20:21], v19, off sc1
.LBB0_1510:
	s_or_b64 exec, exec, s[6:7]
	v_mul_f32_e32 v19, v41, v18
	s_waitcnt lgkmcnt(0)
	ds_bpermute_b32 v20, v84, v19
	s_and_saveexec_b64 s[6:7], vcc
	s_cbranch_execz .LBB0_1512
	s_waitcnt lgkmcnt(0)
	v_cvt_pk_bf16_f32 v19, v19, v20
	v_lshl_add_u64 v[20:21], s[0:1], 0, v[162:163]
	v_mov_b32_e32 v83, v163
	v_lshl_add_u64 v[20:21], v[20:21], 0, v[82:83]
	global_store_dword v[20:21], v19, off offset:64 sc1
.LBB0_1512:
	s_or_b64 exec, exec, s[6:7]
	v_mul_f32_e32 v19, v57, v18
	s_waitcnt lgkmcnt(0)
	ds_bpermute_b32 v20, v84, v19
	s_and_saveexec_b64 s[6:7], vcc
	s_cbranch_execz .LBB0_1514
	s_waitcnt lgkmcnt(0)
	v_cvt_pk_bf16_f32 v19, v19, v20
	v_lshl_add_u64 v[20:21], s[0:1], 0, v[162:163]
	v_mov_b32_e32 v83, v163
	v_lshl_add_u64 v[20:21], v[20:21], 0, v[82:83]
	global_store_dword v[20:21], v19, off offset:128 sc1
.LBB0_1514:
	s_or_b64 exec, exec, s[6:7]
	v_mul_f32_e32 v18, v73, v18
	ds_bpermute_b32 v19, v84, v18
	s_and_saveexec_b64 s[6:7], vcc
	s_cbranch_execz .LBB0_1516
	s_waitcnt lgkmcnt(0)
	v_cvt_pk_bf16_f32 v20, v18, v19
	v_lshl_add_u64 v[18:19], s[0:1], 0, v[162:163]
	v_mov_b32_e32 v83, v163
	v_lshl_add_u64 v[18:19], v[18:19], 0, v[82:83]
	global_store_dword v[18:19], v20, off offset:192 sc1
.LBB0_1516:
	s_or_b64 exec, exec, s[6:7]
	ds_read_b32 v18, v188 offset:64
	v_or_b32_e32 v21, 16, v186
	v_lshlrev_b32_e32 v162, 11, v21
	s_waitcnt lgkmcnt(0)
	v_rcp_f32_e32 v18, v18
	s_nop 0
	v_mul_f32_e32 v19, v26, v18
	ds_bpermute_b32 v20, v84, v19
	s_and_saveexec_b64 s[6:7], vcc
	s_cbranch_execz .LBB0_1518
	s_waitcnt lgkmcnt(0)
	v_cvt_pk_bf16_f32 v19, v19, v20
	v_lshl_add_u64 v[20:21], s[0:1], 0, v[162:163]
	v_mov_b32_e32 v83, v163
	v_lshl_add_u64 v[20:21], v[20:21], 0, v[82:83]
	global_store_dword v[20:21], v19, off sc1
.LBB0_1518:
	s_or_b64 exec, exec, s[6:7]
	v_mul_f32_e32 v19, v42, v18
	s_waitcnt lgkmcnt(0)
	ds_bpermute_b32 v20, v84, v19
	s_and_saveexec_b64 s[6:7], vcc
	s_cbranch_execz .LBB0_1520
	s_waitcnt lgkmcnt(0)
	v_cvt_pk_bf16_f32 v19, v19, v20
	v_lshl_add_u64 v[20:21], s[0:1], 0, v[162:163]
	v_mov_b32_e32 v83, v163
	v_lshl_add_u64 v[20:21], v[20:21], 0, v[82:83]
	global_store_dword v[20:21], v19, off offset:64 sc1
.LBB0_1520:
	s_or_b64 exec, exec, s[6:7]
	v_mul_f32_e32 v19, v58, v18
	s_waitcnt lgkmcnt(0)
	ds_bpermute_b32 v20, v84, v19
	s_and_saveexec_b64 s[6:7], vcc
	s_cbranch_execz .LBB0_1522
	s_waitcnt lgkmcnt(0)
	v_cvt_pk_bf16_f32 v19, v19, v20
	v_lshl_add_u64 v[20:21], s[0:1], 0, v[162:163]
	v_mov_b32_e32 v83, v163
	v_lshl_add_u64 v[20:21], v[20:21], 0, v[82:83]
	global_store_dword v[20:21], v19, off offset:128 sc1
.LBB0_1522:
	s_or_b64 exec, exec, s[6:7]
	v_mul_f32_e32 v18, v74, v18
	ds_bpermute_b32 v19, v84, v18
	s_and_saveexec_b64 s[6:7], vcc
	s_cbranch_execz .LBB0_1524
	s_waitcnt lgkmcnt(0)
	v_cvt_pk_bf16_f32 v20, v18, v19
	v_lshl_add_u64 v[18:19], s[0:1], 0, v[162:163]
	v_mov_b32_e32 v83, v163
	v_lshl_add_u64 v[18:19], v[18:19], 0, v[82:83]
	global_store_dword v[18:19], v20, off offset:192 sc1
.LBB0_1524:
	s_or_b64 exec, exec, s[6:7]
	ds_read_b32 v18, v188 offset:68
	v_or_b32_e32 v21, 17, v186
	v_lshlrev_b32_e32 v162, 11, v21
	s_waitcnt lgkmcnt(0)
	v_rcp_f32_e32 v18, v18
	s_nop 0
	v_mul_f32_e32 v19, v27, v18
	ds_bpermute_b32 v20, v84, v19
	s_and_saveexec_b64 s[6:7], vcc
	s_cbranch_execz .LBB0_1526
	s_waitcnt lgkmcnt(0)
	v_cvt_pk_bf16_f32 v19, v19, v20
	v_lshl_add_u64 v[20:21], s[0:1], 0, v[162:163]
	v_mov_b32_e32 v83, v163
	v_lshl_add_u64 v[20:21], v[20:21], 0, v[82:83]
	global_store_dword v[20:21], v19, off sc1
.LBB0_1526:
	s_or_b64 exec, exec, s[6:7]
	v_mul_f32_e32 v19, v43, v18
	s_waitcnt lgkmcnt(0)
	ds_bpermute_b32 v20, v84, v19
	s_and_saveexec_b64 s[6:7], vcc
	s_cbranch_execz .LBB0_1528
	s_waitcnt lgkmcnt(0)
	v_cvt_pk_bf16_f32 v19, v19, v20
	v_lshl_add_u64 v[20:21], s[0:1], 0, v[162:163]
	v_mov_b32_e32 v83, v163
	v_lshl_add_u64 v[20:21], v[20:21], 0, v[82:83]
	global_store_dword v[20:21], v19, off offset:64 sc1
.LBB0_1528:
	s_or_b64 exec, exec, s[6:7]
	v_mul_f32_e32 v19, v59, v18
	s_waitcnt lgkmcnt(0)
	ds_bpermute_b32 v20, v84, v19
	s_and_saveexec_b64 s[6:7], vcc
	s_cbranch_execz .LBB0_1530
	s_waitcnt lgkmcnt(0)
	v_cvt_pk_bf16_f32 v19, v19, v20
	v_lshl_add_u64 v[20:21], s[0:1], 0, v[162:163]
	v_mov_b32_e32 v83, v163
	v_lshl_add_u64 v[20:21], v[20:21], 0, v[82:83]
	global_store_dword v[20:21], v19, off offset:128 sc1
.LBB0_1530:
	s_or_b64 exec, exec, s[6:7]
	v_mul_f32_e32 v18, v75, v18
	ds_bpermute_b32 v19, v84, v18
	s_and_saveexec_b64 s[6:7], vcc
	s_cbranch_execz .LBB0_1532
	s_waitcnt lgkmcnt(0)
	v_cvt_pk_bf16_f32 v20, v18, v19
	v_lshl_add_u64 v[18:19], s[0:1], 0, v[162:163]
	v_mov_b32_e32 v83, v163
	v_lshl_add_u64 v[18:19], v[18:19], 0, v[82:83]
	global_store_dword v[18:19], v20, off offset:192 sc1
.LBB0_1532:
	s_or_b64 exec, exec, s[6:7]
	ds_read_b32 v18, v188 offset:72
	v_or_b32_e32 v21, 18, v186
	v_lshlrev_b32_e32 v162, 11, v21
	s_waitcnt lgkmcnt(0)
	v_rcp_f32_e32 v18, v18
	s_nop 0
	v_mul_f32_e32 v19, v28, v18
	ds_bpermute_b32 v20, v84, v19
	s_and_saveexec_b64 s[6:7], vcc
	s_cbranch_execz .LBB0_1534
	s_waitcnt lgkmcnt(0)
	v_cvt_pk_bf16_f32 v19, v19, v20
	v_lshl_add_u64 v[20:21], s[0:1], 0, v[162:163]
	v_mov_b32_e32 v83, v163
	v_lshl_add_u64 v[20:21], v[20:21], 0, v[82:83]
	global_store_dword v[20:21], v19, off sc1
.LBB0_1534:
	s_or_b64 exec, exec, s[6:7]
	v_mul_f32_e32 v19, v44, v18
	s_waitcnt lgkmcnt(0)
	ds_bpermute_b32 v20, v84, v19
	s_and_saveexec_b64 s[6:7], vcc
	s_cbranch_execz .LBB0_1536
	s_waitcnt lgkmcnt(0)
	v_cvt_pk_bf16_f32 v19, v19, v20
	v_lshl_add_u64 v[20:21], s[0:1], 0, v[162:163]
	v_mov_b32_e32 v83, v163
	v_lshl_add_u64 v[20:21], v[20:21], 0, v[82:83]
	global_store_dword v[20:21], v19, off offset:64 sc1
.LBB0_1536:
	s_or_b64 exec, exec, s[6:7]
	v_mul_f32_e32 v19, v60, v18
	s_waitcnt lgkmcnt(0)
	ds_bpermute_b32 v20, v84, v19
	s_and_saveexec_b64 s[6:7], vcc
	s_cbranch_execz .LBB0_1538
	s_waitcnt lgkmcnt(0)
	v_cvt_pk_bf16_f32 v19, v19, v20
	v_lshl_add_u64 v[20:21], s[0:1], 0, v[162:163]
	v_mov_b32_e32 v83, v163
	v_lshl_add_u64 v[20:21], v[20:21], 0, v[82:83]
	global_store_dword v[20:21], v19, off offset:128 sc1
.LBB0_1538:
	s_or_b64 exec, exec, s[6:7]
	v_mul_f32_e32 v18, v76, v18
	ds_bpermute_b32 v19, v84, v18
	s_and_saveexec_b64 s[6:7], vcc
	s_cbranch_execz .LBB0_1540
	s_waitcnt lgkmcnt(0)
	v_cvt_pk_bf16_f32 v20, v18, v19
	v_lshl_add_u64 v[18:19], s[0:1], 0, v[162:163]
	v_mov_b32_e32 v83, v163
	v_lshl_add_u64 v[18:19], v[18:19], 0, v[82:83]
	global_store_dword v[18:19], v20, off offset:192 sc1
.LBB0_1540:
	s_or_b64 exec, exec, s[6:7]
	ds_read_b32 v18, v188 offset:76
	v_or_b32_e32 v21, 19, v186
	v_lshlrev_b32_e32 v162, 11, v21
	s_waitcnt lgkmcnt(0)
	v_rcp_f32_e32 v18, v18
	s_nop 0
	v_mul_f32_e32 v19, v29, v18
	ds_bpermute_b32 v20, v84, v19
	s_and_saveexec_b64 s[6:7], vcc
	s_cbranch_execz .LBB0_1542
	s_waitcnt lgkmcnt(0)
	v_cvt_pk_bf16_f32 v19, v19, v20
	v_lshl_add_u64 v[20:21], s[0:1], 0, v[162:163]
	v_mov_b32_e32 v83, v163
	v_lshl_add_u64 v[20:21], v[20:21], 0, v[82:83]
	global_store_dword v[20:21], v19, off sc1
.LBB0_1542:
	s_or_b64 exec, exec, s[6:7]
	v_mul_f32_e32 v19, v45, v18
	s_waitcnt lgkmcnt(0)
	ds_bpermute_b32 v20, v84, v19
	s_and_saveexec_b64 s[6:7], vcc
	s_cbranch_execz .LBB0_1544
	s_waitcnt lgkmcnt(0)
	v_cvt_pk_bf16_f32 v19, v19, v20
	v_lshl_add_u64 v[20:21], s[0:1], 0, v[162:163]
	v_mov_b32_e32 v83, v163
	v_lshl_add_u64 v[20:21], v[20:21], 0, v[82:83]
	global_store_dword v[20:21], v19, off offset:64 sc1
.LBB0_1544:
	s_or_b64 exec, exec, s[6:7]
	v_mul_f32_e32 v19, v61, v18
	s_waitcnt lgkmcnt(0)
	ds_bpermute_b32 v20, v84, v19
	s_and_saveexec_b64 s[6:7], vcc
	s_cbranch_execz .LBB0_1546
	s_waitcnt lgkmcnt(0)
	v_cvt_pk_bf16_f32 v19, v19, v20
	v_lshl_add_u64 v[20:21], s[0:1], 0, v[162:163]
	v_mov_b32_e32 v83, v163
	v_lshl_add_u64 v[20:21], v[20:21], 0, v[82:83]
	global_store_dword v[20:21], v19, off offset:128 sc1
.LBB0_1546:
	s_or_b64 exec, exec, s[6:7]
	v_mul_f32_e32 v18, v77, v18
	ds_bpermute_b32 v19, v84, v18
	s_and_saveexec_b64 s[6:7], vcc
	s_cbranch_execz .LBB0_1548
	s_waitcnt lgkmcnt(0)
	v_cvt_pk_bf16_f32 v20, v18, v19
	v_lshl_add_u64 v[18:19], s[0:1], 0, v[162:163]
	v_mov_b32_e32 v83, v163
	v_lshl_add_u64 v[18:19], v[18:19], 0, v[82:83]
	global_store_dword v[18:19], v20, off offset:192 sc1
.LBB0_1548:
	s_or_b64 exec, exec, s[6:7]
	ds_read_b32 v18, v188 offset:96
	v_or_b32_e32 v21, 24, v186
	v_lshlrev_b32_e32 v162, 11, v21
	s_waitcnt lgkmcnt(0)
	v_rcp_f32_e32 v18, v18
	s_nop 0
	v_mul_f32_e32 v19, v30, v18
	ds_bpermute_b32 v20, v84, v19
	s_and_saveexec_b64 s[6:7], vcc
	s_cbranch_execz .LBB0_1550
	s_waitcnt lgkmcnt(0)
	v_cvt_pk_bf16_f32 v19, v19, v20
	v_lshl_add_u64 v[20:21], s[0:1], 0, v[162:163]
	v_mov_b32_e32 v83, v163
	v_lshl_add_u64 v[20:21], v[20:21], 0, v[82:83]
	global_store_dword v[20:21], v19, off sc1
.LBB0_1550:
	s_or_b64 exec, exec, s[6:7]
	v_mul_f32_e32 v19, v46, v18
	s_waitcnt lgkmcnt(0)
	ds_bpermute_b32 v20, v84, v19
	s_and_saveexec_b64 s[6:7], vcc
	s_cbranch_execz .LBB0_1552
	s_waitcnt lgkmcnt(0)
	v_cvt_pk_bf16_f32 v19, v19, v20
	v_lshl_add_u64 v[20:21], s[0:1], 0, v[162:163]
	v_mov_b32_e32 v83, v163
	v_lshl_add_u64 v[20:21], v[20:21], 0, v[82:83]
	global_store_dword v[20:21], v19, off offset:64 sc1
.LBB0_1552:
	s_or_b64 exec, exec, s[6:7]
	v_mul_f32_e32 v19, v62, v18
	s_waitcnt lgkmcnt(0)
	ds_bpermute_b32 v20, v84, v19
	s_and_saveexec_b64 s[6:7], vcc
	s_cbranch_execz .LBB0_1554
	s_waitcnt lgkmcnt(0)
	v_cvt_pk_bf16_f32 v19, v19, v20
	v_lshl_add_u64 v[20:21], s[0:1], 0, v[162:163]
	v_mov_b32_e32 v83, v163
	v_lshl_add_u64 v[20:21], v[20:21], 0, v[82:83]
	global_store_dword v[20:21], v19, off offset:128 sc1
.LBB0_1554:
	s_or_b64 exec, exec, s[6:7]
	v_mul_f32_e32 v18, v78, v18
	ds_bpermute_b32 v19, v84, v18
	s_and_saveexec_b64 s[6:7], vcc
	s_cbranch_execz .LBB0_1556
	s_waitcnt lgkmcnt(0)
	v_cvt_pk_bf16_f32 v20, v18, v19
	v_lshl_add_u64 v[18:19], s[0:1], 0, v[162:163]
	v_mov_b32_e32 v83, v163
	v_lshl_add_u64 v[18:19], v[18:19], 0, v[82:83]
	global_store_dword v[18:19], v20, off offset:192 sc1
.LBB0_1556:
	s_or_b64 exec, exec, s[6:7]
	ds_read_b32 v18, v188 offset:100
	v_or_b32_e32 v21, 25, v186
	v_lshlrev_b32_e32 v162, 11, v21
	s_waitcnt lgkmcnt(0)
	v_rcp_f32_e32 v18, v18
	s_nop 0
	v_mul_f32_e32 v19, v31, v18
	ds_bpermute_b32 v20, v84, v19
	s_and_saveexec_b64 s[6:7], vcc
	s_cbranch_execz .LBB0_1558
	s_waitcnt lgkmcnt(0)
	v_cvt_pk_bf16_f32 v19, v19, v20
	v_lshl_add_u64 v[20:21], s[0:1], 0, v[162:163]
	v_mov_b32_e32 v83, v163
	v_lshl_add_u64 v[20:21], v[20:21], 0, v[82:83]
	global_store_dword v[20:21], v19, off sc1
.LBB0_1558:
	s_or_b64 exec, exec, s[6:7]
	v_mul_f32_e32 v19, v47, v18
	s_waitcnt lgkmcnt(0)
	ds_bpermute_b32 v20, v84, v19
	s_and_saveexec_b64 s[6:7], vcc
	s_cbranch_execz .LBB0_1560
	s_waitcnt lgkmcnt(0)
	v_cvt_pk_bf16_f32 v19, v19, v20
	v_lshl_add_u64 v[20:21], s[0:1], 0, v[162:163]
	v_mov_b32_e32 v83, v163
	v_lshl_add_u64 v[20:21], v[20:21], 0, v[82:83]
	global_store_dword v[20:21], v19, off offset:64 sc1
.LBB0_1560:
	s_or_b64 exec, exec, s[6:7]
	v_mul_f32_e32 v19, v63, v18
	s_waitcnt lgkmcnt(0)
	ds_bpermute_b32 v20, v84, v19
	s_and_saveexec_b64 s[6:7], vcc
	s_cbranch_execz .LBB0_1562
	s_waitcnt lgkmcnt(0)
	v_cvt_pk_bf16_f32 v19, v19, v20
	v_lshl_add_u64 v[20:21], s[0:1], 0, v[162:163]
	v_mov_b32_e32 v83, v163
	v_lshl_add_u64 v[20:21], v[20:21], 0, v[82:83]
	global_store_dword v[20:21], v19, off offset:128 sc1
.LBB0_1562:
	s_or_b64 exec, exec, s[6:7]
	v_mul_f32_e32 v18, v79, v18
	ds_bpermute_b32 v19, v84, v18
	s_and_saveexec_b64 s[6:7], vcc
	s_cbranch_execz .LBB0_1564
	s_waitcnt lgkmcnt(0)
	v_cvt_pk_bf16_f32 v20, v18, v19
	v_lshl_add_u64 v[18:19], s[0:1], 0, v[162:163]
	v_mov_b32_e32 v83, v163
	v_lshl_add_u64 v[18:19], v[18:19], 0, v[82:83]
	global_store_dword v[18:19], v20, off offset:192 sc1
.LBB0_1564:
	s_or_b64 exec, exec, s[6:7]
	ds_read_b32 v18, v188 offset:104
	v_or_b32_e32 v21, 26, v186
	v_lshlrev_b32_e32 v162, 11, v21
	s_waitcnt lgkmcnt(0)
	v_rcp_f32_e32 v18, v18
	s_nop 0
	v_mul_f32_e32 v19, v32, v18
	ds_bpermute_b32 v20, v84, v19
	s_and_saveexec_b64 s[6:7], vcc
	s_cbranch_execz .LBB0_1566
	s_waitcnt lgkmcnt(0)
	v_cvt_pk_bf16_f32 v19, v19, v20
	v_lshl_add_u64 v[20:21], s[0:1], 0, v[162:163]
	v_mov_b32_e32 v83, v163
	v_lshl_add_u64 v[20:21], v[20:21], 0, v[82:83]
	global_store_dword v[20:21], v19, off sc1
.LBB0_1566:
	s_or_b64 exec, exec, s[6:7]
	v_mul_f32_e32 v19, v48, v18
	s_waitcnt lgkmcnt(0)
	ds_bpermute_b32 v20, v84, v19
	s_and_saveexec_b64 s[6:7], vcc
	s_cbranch_execz .LBB0_1568
	s_waitcnt lgkmcnt(0)
	v_cvt_pk_bf16_f32 v19, v19, v20
	v_lshl_add_u64 v[20:21], s[0:1], 0, v[162:163]
	v_mov_b32_e32 v83, v163
	v_lshl_add_u64 v[20:21], v[20:21], 0, v[82:83]
	global_store_dword v[20:21], v19, off offset:64 sc1
.LBB0_1568:
	s_or_b64 exec, exec, s[6:7]
	v_mul_f32_e32 v19, v64, v18
	s_waitcnt lgkmcnt(0)
	ds_bpermute_b32 v20, v84, v19
	s_and_saveexec_b64 s[6:7], vcc
	s_cbranch_execz .LBB0_1570
	s_waitcnt lgkmcnt(0)
	v_cvt_pk_bf16_f32 v19, v19, v20
	v_lshl_add_u64 v[20:21], s[0:1], 0, v[162:163]
	v_mov_b32_e32 v83, v163
	v_lshl_add_u64 v[20:21], v[20:21], 0, v[82:83]
	global_store_dword v[20:21], v19, off offset:128 sc1
.LBB0_1570:
	s_or_b64 exec, exec, s[6:7]
	v_mul_f32_e32 v18, v80, v18
	ds_bpermute_b32 v19, v84, v18
	s_and_saveexec_b64 s[6:7], vcc
	s_cbranch_execz .LBB0_1572
	s_waitcnt lgkmcnt(0)
	v_cvt_pk_bf16_f32 v20, v18, v19
	v_lshl_add_u64 v[18:19], s[0:1], 0, v[162:163]
	v_mov_b32_e32 v83, v163
	v_lshl_add_u64 v[18:19], v[18:19], 0, v[82:83]
	global_store_dword v[18:19], v20, off offset:192 sc1
.LBB0_1572:
	s_or_b64 exec, exec, s[6:7]
	ds_read_b32 v18, v188 offset:108
	v_or_b32_e32 v21, 27, v186
	v_lshlrev_b32_e32 v162, 11, v21
	s_waitcnt lgkmcnt(0)
	v_rcp_f32_e32 v18, v18
	s_nop 0
	v_mul_f32_e32 v19, v33, v18
	ds_bpermute_b32 v20, v84, v19
	s_and_saveexec_b64 s[6:7], vcc
	s_cbranch_execz .LBB0_1574
	s_waitcnt lgkmcnt(0)
	v_cvt_pk_bf16_f32 v19, v19, v20
	v_lshl_add_u64 v[20:21], s[0:1], 0, v[162:163]
	v_mov_b32_e32 v83, v163
	v_lshl_add_u64 v[20:21], v[20:21], 0, v[82:83]
	global_store_dword v[20:21], v19, off sc1
.LBB0_1574:
	s_or_b64 exec, exec, s[6:7]
	v_mul_f32_e32 v19, v49, v18
	s_waitcnt lgkmcnt(0)
	ds_bpermute_b32 v20, v84, v19
	s_and_saveexec_b64 s[6:7], vcc
	s_cbranch_execz .LBB0_1576
	s_waitcnt lgkmcnt(0)
	v_cvt_pk_bf16_f32 v19, v19, v20
	v_lshl_add_u64 v[20:21], s[0:1], 0, v[162:163]
	v_mov_b32_e32 v83, v163
	v_lshl_add_u64 v[20:21], v[20:21], 0, v[82:83]
	global_store_dword v[20:21], v19, off offset:64 sc1
.LBB0_1576:
	s_or_b64 exec, exec, s[6:7]
	v_mul_f32_e32 v19, v65, v18
	s_waitcnt lgkmcnt(0)
	ds_bpermute_b32 v20, v84, v19
	s_and_saveexec_b64 s[6:7], vcc
	s_cbranch_execz .LBB0_1578
	s_waitcnt lgkmcnt(0)
	v_cvt_pk_bf16_f32 v19, v19, v20
	v_lshl_add_u64 v[20:21], s[0:1], 0, v[162:163]
	v_mov_b32_e32 v83, v163
	v_lshl_add_u64 v[20:21], v[20:21], 0, v[82:83]
	global_store_dword v[20:21], v19, off offset:128 sc1
.LBB0_1578:
	s_or_b64 exec, exec, s[6:7]
	v_mul_f32_e32 v18, v81, v18
	ds_bpermute_b32 v19, v84, v18
	s_and_saveexec_b64 s[6:7], vcc
	s_cbranch_execz .LBB0_1421
	s_waitcnt lgkmcnt(0)
	v_cvt_pk_bf16_f32 v20, v18, v19
	v_lshl_add_u64 v[18:19], s[0:1], 0, v[162:163]
	v_mov_b32_e32 v83, v163
	v_lshl_add_u64 v[18:19], v[18:19], 0, v[82:83]
	global_store_dword v[18:19], v20, off offset:192 sc1
	s_branch .LBB0_1421
